# v12 plus counted vmcnt(16) in the first two K-loop epochs after a P1 epilogue (8 stores may stay in flight; first unit keeps vmcnt 8)
# baseline (speedup 1.0000x reference)
; #define PG8_STAGE(bufoff, gbase, voff) do { _Pragma("unroll") for (int _i = 0; _i < 2; ++_i) \
;         __builtin_amdgcn_global_load_lds((const unsigned*)((const char*)(gbase) + (voff)[_i]), (LAS unsigned*)(lds + (bufoff) + ldsw + _i * 8192), 16, 0, 0); } while (0)
; #define PG8_LDA(dst, b, h) do { _Pragma("unroll") for (int m = 0; m < 4; ++m) _Pragma("unroll") for (int k = 0; k < 2; ++k) dst[m][k] = *(const LAS bf16x8*)(lds + PG8_SA(b, h) + aoff + m * 2048 + k * 1024); } while (0)
; #define PG8_LDB(dst, b, h) do { _Pragma("unroll") for (int n = 0; n < 2; ++n) _Pragma("unroll") for (int k = 0; k < 2; ++k) dst[n][k] = *(const LAS bf16x8*)(lds + PG8_SB(b, h) + boff + n * 2048 + k * 1024); } while (0)
; #define PG8_MMA(ai, bj, At, Bt) do { __builtin_amdgcn_s_setprio(1); _Pragma("unroll") for (int m = 0; m < 4; ++m) _Pragma("unroll") for (int n = 0; n < 2; ++n) _Pragma("unroll") for (int k = 0; k < 2; ++k) \
;         acc[ai][bj][m][n] = __builtin_amdgcn_mfma_f32_16x16x32_bf16(Bt[n][k], At[m][k], acc[ai][bj][m][n], 0, 0, 0); __builtin_amdgcn_s_setprio(0); } while (0)
; #define PG8_WAIT_V(n) asm volatile("s_waitcnt vmcnt(" #n ")" ::: "memory")
; #define PG8_WAIT_L(n) asm volatile("s_waitcnt lgkmcnt(" #n ")" ::: "memory")
; #define PG8_BAR __builtin_amdgcn_s_barrier()
; #define PG8_SCHED __builtin_amdgcn_sched_barrier(0)
; template <class Epi, class Sched, int NSEG, bool ALIGN_EPI = true, bool AFTER_DRAIN = false>
; __device__ __forceinline__ void gemm_phase(LAS unsigned char* lds, const Gemm g, const Sched& S, const Epi& E) {
;     ...
;         const bool has_next = S.next(ui + 1, nxt);
;         const char* nA = has_next ? PG8_ABASE(nxt) : cA; const char* nB = has_next ? PG8_BBASE(nxt) : cB;
;         for (int t = 0; t < nt; t += 2) {
;             const bool last = (t == nt - 2);
;             const char* a1 = cA + (size_t)(t + 1) * kstep;
;             const char* a2 = last ? nA : cA + (size_t)(t + 2) * kstep; const char* b2 = last ? nB : cB + (size_t)(t + 2) * kstep;
;             const char* a3 = a2 + kstep; const char* b3 = b2 + kstep;
;             PG8_LDB(B0, 0, 0); PG8_LDB(B1, 0, 1); PG8_SCHED; PG8_LDA(At, 0, 0); PG8_STAGE(PG8_SA(1, 1), a1 + hstep, voffA);
;             PG8_WAIT_V(8); PG8_WAIT_L(0); PG8_BAR; PG8_MMA(0, 0, At, B0); PG8_MMA(0, 1, At, B1); PG8_BAR; PG8_SCHED;
.LBB0_326:
	ds_read_b128 v[192:195], v164 offset:0
	ds_read_b128 v[196:199], v164 offset:1024
	ds_read_b128 v[200:203], v164 offset:2048
	ds_read_b128 v[204:207], v164 offset:3072
	ds_read_b128 v[208:211], v164 offset:4096
	ds_read_b128 v[212:215], v164 offset:5120
	ds_read_b128 v[216:219], v164 offset:6144
	ds_read_b128 v[220:223], v164 offset:7168
	ds_read_b128 v[128:131], v162 offset:0
	ds_read_b128 v[132:135], v162 offset:1024
	ds_read_b128 v[166:169], v162 offset:2048
	ds_read_b128 v[170:173], v162 offset:3072
	s_ashr_i32 s19, s18, 31
	s_lshl_b64 s[20:21], s[18:19], 20
	s_add_u32 s20, s4, s20
	s_addc_u32 s21, s5, s21
	v_readlane_b32 s52, v248, 29
	s_and_b64 s[22:23], s[0:1], exec
	v_readlane_b32 s53, v248, 30
	v_readlane_b32 s54, v248, 31
	v_readlane_b32 s55, v248, 32
	v_readlane_b32 s56, v248, 33
	v_readlane_b32 s57, v248, 34
	s_cselect_b32 s3, s21, s27
	s_cselect_b32 s19, s20, s26
	s_ashr_i32 s17, s16, 31
	v_readlane_b32 s58, v248, 35
	v_readlane_b32 s59, v248, 36
	s_mov_b64 s[52:53], s[56:57]
	s_lshl_b64 s[22:23], s[16:17], 20
	s_mov_b64 s[54:55], s[58:59]
	s_add_u32 s22, s54, s22
	s_addc_u32 s23, s55, s23
	s_and_b64 s[30:31], s[0:1], exec
	s_cselect_b32 s17, s23, s29
	s_cselect_b32 s25, s22, s28
	s_waitcnt lgkmcnt(0)
	s_barrier
	s_add_u32 s74, s72, 0x80000
	s_addc_u32 s75, s73, 0
	s_add_u32 s78, s76, 0x80000
	s_addc_u32 s79, s77, 0
	v_mfma_f32_16x16x32_bf16 v[124:127], v[128:131], v[192:195], 0
	ds_read_b128 v[174:177], v162 offset:16384
	v_mfma_f32_16x16x32_bf16 v[120:123], v[166:169], v[192:195], 0
	ds_read_b128 v[178:181], v162 offset:17408
	v_mfma_f32_16x16x32_bf16 v[108:111], v[128:131], v[200:203], 0
	ds_read_b128 v[182:185], v162 offset:18432
	v_mfma_f32_16x16x32_bf16 v[104:107], v[166:169], v[200:203], 0
	ds_read_b128 v[188:191], v162 offset:19456
	v_mfma_f32_16x16x32_bf16 v[92:95], v[128:131], v[208:211], 0
	s_mov_b32 m0, s33
	v_mfma_f32_16x16x32_bf16 v[88:91], v[166:169], v[208:211], 0
	global_load_lds_dwordx4 v138, s[72:73]
	v_mfma_f32_16x16x32_bf16 v[76:79], v[128:131], v[216:219], 0
	ds_read_b128 v[224:227], v164 offset:16384
	v_mfma_f32_16x16x32_bf16 v[72:75], v[166:169], v[216:219], 0
	ds_read_b128 v[228:231], v164 offset:17408
	v_mfma_f32_16x16x32_bf16 v[124:127], v[132:135], v[196:199], v[124:127]
	ds_read_b128 v[232:235], v164 offset:18432
	v_mfma_f32_16x16x32_bf16 v[120:123], v[170:173], v[196:199], v[120:123]
	ds_read_b128 v[236:239], v164 offset:19456
	v_mfma_f32_16x16x32_bf16 v[108:111], v[132:135], v[204:207], v[108:111]
	s_add_i32 m0, s33, 0x2000
	v_mfma_f32_16x16x32_bf16 v[104:107], v[170:173], v[204:207], v[104:107]
	global_load_lds_dwordx4 v142, s[72:73]
	v_mfma_f32_16x16x32_bf16 v[92:95], v[132:135], v[212:215], v[92:95]
	ds_read_b128 v[240:243], v164 offset:20480
	v_mfma_f32_16x16x32_bf16 v[88:91], v[170:173], v[212:215], v[88:91]
	ds_read_b128 v[244:247], v164 offset:21504
	v_mfma_f32_16x16x32_bf16 v[76:79], v[132:135], v[220:223], v[76:79]
	ds_read_b128 v[250:253], v164 offset:22528
	v_mfma_f32_16x16x32_bf16 v[72:75], v[170:173], v[220:223], v[72:75]
	ds_read_b128 v[150:153], v164 offset:23552
	s_waitcnt lgkmcnt(8)
	v_mfma_f32_16x16x32_bf16 v[116:119], v[174:177], v[192:195], 0
	s_add_i32 m0, s33, 0x10000
	v_mfma_f32_16x16x32_bf16 v[112:115], v[182:185], v[192:195], 0
	global_load_lds_dwordx4 v140, s[76:77]
	v_mfma_f32_16x16x32_bf16 v[100:103], v[174:177], v[200:203], 0
	v_mfma_f32_16x16x32_bf16 v[96:99], v[182:185], v[200:203], 0
	v_mfma_f32_16x16x32_bf16 v[84:87], v[174:177], v[208:211], 0
	s_add_i32 m0, s33, 0x12000
	v_mfma_f32_16x16x32_bf16 v[80:83], v[182:185], v[208:211], 0
	global_load_lds_dwordx4 v144, s[76:77]
	v_mfma_f32_16x16x32_bf16 v[68:71], v[174:177], v[216:219], 0
	v_mfma_f32_16x16x32_bf16 v[64:67], v[182:185], v[216:219], 0
	v_mfma_f32_16x16x32_bf16 v[116:119], v[178:181], v[196:199], v[116:119]
	v_mfma_f32_16x16x32_bf16 v[112:115], v[188:191], v[196:199], v[112:115]
	v_mfma_f32_16x16x32_bf16 v[100:103], v[178:181], v[204:207], v[100:103]
	v_mfma_f32_16x16x32_bf16 v[96:99], v[188:191], v[204:207], v[96:99]
	v_mfma_f32_16x16x32_bf16 v[84:87], v[178:181], v[212:215], v[84:87]
	v_mfma_f32_16x16x32_bf16 v[80:83], v[188:191], v[212:215], v[80:83]
	v_mfma_f32_16x16x32_bf16 v[68:71], v[178:181], v[220:223], v[68:71]
	v_mfma_f32_16x16x32_bf16 v[64:67], v[188:191], v[220:223], v[64:67]
	s_cmp_lg_u32 s37, 1
	s_cbranch_scc1 .Lp1_kloop_rp
	s_waitcnt vmcnt(8) lgkmcnt(0)
	s_branch .Lp1_kloop_dp
; #define PG8_STAGE(bufoff, gbase, voff) do { _Pragma("unroll") for (int _i = 0; _i < 2; ++_i) \
;         __builtin_amdgcn_global_load_lds((const unsigned*)((const char*)(gbase) + (voff)[_i]), (LAS unsigned*)(lds + (bufoff) + ldsw + _i * 8192), 16, 0, 0); } while (0)
; #define PG8_LDA(dst, b, h) do { _Pragma("unroll") for (int m = 0; m < 4; ++m) _Pragma("unroll") for (int k = 0; k < 2; ++k) dst[m][k] = *(const LAS bf16x8*)(lds + PG8_SA(b, h) + aoff + m * 2048 + k * 1024); } while (0)
; #define PG8_MMA(ai, bj, At, Bt) do { __builtin_amdgcn_s_setprio(1); _Pragma("unroll") for (int m = 0; m < 4; ++m) _Pragma("unroll") for (int n = 0; n < 2; ++n) _Pragma("unroll") for (int k = 0; k < 2; ++k) \
;         acc[ai][bj][m][n] = __builtin_amdgcn_mfma_f32_16x16x32_bf16(Bt[n][k], At[m][k], acc[ai][bj][m][n], 0, 0, 0); __builtin_amdgcn_s_setprio(0); } while (0)
; #define PG8_WAIT_V(n) asm volatile("s_waitcnt vmcnt(" #n ")" ::: "memory")
; #define PG8_WAIT_L(n) asm volatile("s_waitcnt lgkmcnt(" #n ")" ::: "memory")
; #define PG8_BAR __builtin_amdgcn_s_barrier()
; #define PG8_SCHED __builtin_amdgcn_sched_barrier(0)
; template <class Epi, class Sched, int NSEG, bool ALIGN_EPI = true, bool AFTER_DRAIN = false>
; __device__ __forceinline__ void gemm_phase(LAS unsigned char* lds, const Gemm g, const Sched& S, const Epi& E) {
;     ...
;             PG8_WAIT_V(8); PG8_WAIT_L(0); PG8_BAR; PG8_MMA(0, 0, At, B0); PG8_MMA(0, 1, At, B1); PG8_BAR; PG8_SCHED;
;             PG8_LDA(At, 0, 1); PG8_STAGE(PG8_SB(0, 0), b2, voffB); PG8_STAGE(PG8_SB(0, 1), b2 + hstep, voffB); PG8_STAGE(PG8_SA(0, 0), a2, voffA);
;             PG8_WAIT_V(8); PG8_WAIT_L(0); PG8_BAR; PG8_MMA(1, 0, At, B0); PG8_MMA(1, 1, At, B1); PG8_BAR; PG8_SCHED;
.Lp1_kloop_rp:
	s_waitcnt vmcnt(16) lgkmcnt(0)
.Lp1_kloop_dp:
	s_barrier
	v_mfma_f32_16x16x32_bf16 v[60:63], v[128:131], v[224:227], 0
	ds_read_b128 v[192:195], v164 offset:32768
	v_mfma_f32_16x16x32_bf16 v[56:59], v[166:169], v[224:227], 0
	ds_read_b128 v[196:199], v164 offset:33792
	v_mfma_f32_16x16x32_bf16 v[44:47], v[128:131], v[232:235], 0
	ds_read_b128 v[200:203], v164 offset:34816
	v_mfma_f32_16x16x32_bf16 v[40:43], v[166:169], v[232:235], 0
	ds_read_b128 v[204:207], v164 offset:35840
	v_mfma_f32_16x16x32_bf16 v[28:31], v[128:131], v[240:243], 0
	ds_read_b128 v[208:211], v164 offset:36864
	v_mfma_f32_16x16x32_bf16 v[24:27], v[166:169], v[240:243], 0
	ds_read_b128 v[212:215], v164 offset:37888
	v_mfma_f32_16x16x32_bf16 v[12:15], v[128:131], v[250:253], 0
	ds_read_b128 v[216:219], v164 offset:38912
	v_mfma_f32_16x16x32_bf16 v[8:11], v[166:169], v[250:253], 0
	ds_read_b128 v[220:223], v164 offset:39936
	v_mfma_f32_16x16x32_bf16 v[60:63], v[132:135], v[228:231], v[60:63]
	s_add_i32 m0, s33, 0x4000
	v_mfma_f32_16x16x32_bf16 v[56:59], v[170:173], v[228:231], v[56:59]
	global_load_lds_dwordx4 v138, s[74:75]
	v_mfma_f32_16x16x32_bf16 v[44:47], v[132:135], v[236:239], v[44:47]
	v_mfma_f32_16x16x32_bf16 v[40:43], v[170:173], v[236:239], v[40:43]
	v_mfma_f32_16x16x32_bf16 v[28:31], v[132:135], v[244:247], v[28:31]
	s_add_i32 m0, s33, 0x6000
	v_mfma_f32_16x16x32_bf16 v[24:27], v[170:173], v[244:247], v[24:27]
	global_load_lds_dwordx4 v142, s[74:75]
	v_mfma_f32_16x16x32_bf16 v[12:15], v[132:135], v[150:153], v[12:15]
	v_mfma_f32_16x16x32_bf16 v[8:11], v[170:173], v[150:153], v[8:11]
	v_mfma_f32_16x16x32_bf16 v[52:55], v[174:177], v[224:227], 0
	ds_read_b128 v[128:131], v162 offset:32768
	v_mfma_f32_16x16x32_bf16 v[48:51], v[182:185], v[224:227], 0
	ds_read_b128 v[132:135], v162 offset:33792
	v_mfma_f32_16x16x32_bf16 v[36:39], v[174:177], v[232:235], 0
	ds_read_b128 v[166:169], v162 offset:34816
	v_mfma_f32_16x16x32_bf16 v[32:35], v[182:185], v[232:235], 0
	ds_read_b128 v[170:173], v162 offset:35840
	v_mfma_f32_16x16x32_bf16 v[20:23], v[174:177], v[240:243], 0
	s_add_i32 m0, s33, 0x14000
	v_mfma_f32_16x16x32_bf16 v[16:19], v[182:185], v[240:243], 0
	global_load_lds_dwordx4 v140, s[78:79]
	v_mfma_f32_16x16x32_bf16 v[4:7], v[174:177], v[250:253], 0
	v_mfma_f32_16x16x32_bf16 v[0:3], v[182:185], v[250:253], 0
	v_mfma_f32_16x16x32_bf16 v[52:55], v[178:181], v[228:231], v[52:55]
	s_add_i32 m0, s33, 0x16000
	v_mfma_f32_16x16x32_bf16 v[48:51], v[188:191], v[228:231], v[48:51]
	global_load_lds_dwordx4 v144, s[78:79]
	v_mfma_f32_16x16x32_bf16 v[36:39], v[178:181], v[236:239], v[36:39]
	v_mfma_f32_16x16x32_bf16 v[32:35], v[188:191], v[236:239], v[32:35]
	v_mfma_f32_16x16x32_bf16 v[20:23], v[178:181], v[244:247], v[20:23]
	v_mfma_f32_16x16x32_bf16 v[16:19], v[188:191], v[244:247], v[16:19]
	v_mfma_f32_16x16x32_bf16 v[4:7], v[178:181], v[150:153], v[4:7]
	v_mfma_f32_16x16x32_bf16 v[0:3], v[188:191], v[150:153], v[0:3]
	s_cmp_lg_u32 s37, 1
	s_cbranch_scc1 .Lp1_kloop_rq
	s_waitcnt vmcnt(8) lgkmcnt(0)
	s_branch .Lp1_kloop_dq

; #define PG8_STAGE(bufoff, gbase, voff) do { _Pragma("unroll") for (int _i = 0; _i < 2; ++_i) \
;         __builtin_amdgcn_global_load_lds((const unsigned*)((const char*)(gbase) + (voff)[_i]), (LAS unsigned*)(lds + (bufoff) + ldsw + _i * 8192), 16, 0, 0); } while (0)
; #define PG8_LDA(dst, b, h) do { _Pragma("unroll") for (int m = 0; m < 4; ++m) _Pragma("unroll") for (int k = 0; k < 2; ++k) dst[m][k] = *(const LAS bf16x8*)(lds + PG8_SA(b, h) + aoff + m * 2048 + k * 1024); } while (0)
; #define PG8_LDB(dst, b, h) do { _Pragma("unroll") for (int n = 0; n < 2; ++n) _Pragma("unroll") for (int k = 0; k < 2; ++k) dst[n][k] = *(const LAS bf16x8*)(lds + PG8_SB(b, h) + boff + n * 2048 + k * 1024); } while (0)
; #define PG8_MMA(ai, bj, At, Bt) do { __builtin_amdgcn_s_setprio(1); _Pragma("unroll") for (int m = 0; m < 4; ++m) _Pragma("unroll") for (int n = 0; n < 2; ++n) _Pragma("unroll") for (int k = 0; k < 2; ++k) \
;         acc[ai][bj][m][n] = __builtin_amdgcn_mfma_f32_16x16x32_bf16(Bt[n][k], At[m][k], acc[ai][bj][m][n], 0, 0, 0); __builtin_amdgcn_s_setprio(0); } while (0)
; #define PG8_WAIT_V(n) asm volatile("s_waitcnt vmcnt(" #n ")" ::: "memory")
; #define PG8_WAIT_L(n) asm volatile("s_waitcnt lgkmcnt(" #n ")" ::: "memory")
; #define PG8_BAR __builtin_amdgcn_s_barrier()
; #define PG8_SCHED __builtin_amdgcn_sched_barrier(0)
; template <class Epi, class Sched, int NSEG, bool ALIGN_EPI = true, bool AFTER_DRAIN = false>
; __device__ __forceinline__ void gemm_phase(LAS unsigned char* lds, const Gemm g, const Sched& S, const Epi& E) {
;     ...
;             PG8_WAIT_V(8); PG8_WAIT_L(0); PG8_BAR; PG8_MMA(1, 0, At, B0); PG8_MMA(1, 1, At, B1); PG8_BAR; PG8_SCHED;
;             PG8_LDB(B0, 1, 0); PG8_LDB(B1, 1, 1); PG8_SCHED; PG8_LDA(At, 1, 0); PG8_STAGE(PG8_SA(0, 1), a2 + hstep, voffA);
;             PG8_WAIT_V(8); PG8_WAIT_L(0); PG8_BAR; PG8_MMA(0, 0, At, B0); PG8_MMA(0, 1, At, B1); PG8_BAR; PG8_SCHED;
;             PG8_LDA(At, 1, 1); PG8_STAGE(PG8_SB(1, 0), b3, voffB); PG8_STAGE(PG8_SB(1, 1), b3 + hstep, voffB); PG8_STAGE(PG8_SA(1, 0), a3, voffA);
;             PG8_WAIT_V(8); PG8_WAIT_L(0); PG8_BAR; PG8_MMA(1, 0, At, B0); PG8_MMA(1, 1, At, B1); PG8_BAR; PG8_SCHED;
.Lp1_kloop_dq:
	s_barrier
	v_mfma_f32_16x16x32_bf16 v[124:127], v[128:131], v[192:195], v[124:127]
	ds_read_b128 v[174:177], v162 offset:49152
	s_add_u32 s72, s72, 0x80
	s_addc_u32 s73, s73, 0
	v_mfma_f32_16x16x32_bf16 v[120:123], v[166:169], v[192:195], v[120:123]
	ds_read_b128 v[178:181], v162 offset:50176
	s_add_u32 s76, s76, 0x80
	s_addc_u32 s77, s77, 0
	v_mfma_f32_16x16x32_bf16 v[108:111], v[128:131], v[200:203], v[108:111]
	ds_read_b128 v[182:185], v162 offset:51200
	v_mfma_f32_16x16x32_bf16 v[104:107], v[166:169], v[200:203], v[104:107]
	ds_read_b128 v[188:191], v162 offset:52224
	v_mfma_f32_16x16x32_bf16 v[92:95], v[128:131], v[208:211], v[92:95]
	s_add_i32 m0, s33, 0x8000
	v_mfma_f32_16x16x32_bf16 v[88:91], v[166:169], v[208:211], v[88:91]
	global_load_lds_dwordx4 v138, s[72:73]
	v_mfma_f32_16x16x32_bf16 v[76:79], v[128:131], v[216:219], v[76:79]
	ds_read_b128 v[224:227], v164 offset:49152
	v_mfma_f32_16x16x32_bf16 v[72:75], v[166:169], v[216:219], v[72:75]
	ds_read_b128 v[228:231], v164 offset:50176
	v_mfma_f32_16x16x32_bf16 v[124:127], v[132:135], v[196:199], v[124:127]
	ds_read_b128 v[232:235], v164 offset:51200
	v_mfma_f32_16x16x32_bf16 v[120:123], v[170:173], v[196:199], v[120:123]
	ds_read_b128 v[236:239], v164 offset:52224
	v_mfma_f32_16x16x32_bf16 v[108:111], v[132:135], v[204:207], v[108:111]
	s_add_i32 m0, s33, 0xa000
	v_mfma_f32_16x16x32_bf16 v[104:107], v[170:173], v[204:207], v[104:107]
	global_load_lds_dwordx4 v142, s[72:73]
	v_mfma_f32_16x16x32_bf16 v[92:95], v[132:135], v[212:215], v[92:95]
	ds_read_b128 v[240:243], v164 offset:53248
	v_mfma_f32_16x16x32_bf16 v[88:91], v[170:173], v[212:215], v[88:91]
	ds_read_b128 v[244:247], v164 offset:54272
	v_mfma_f32_16x16x32_bf16 v[76:79], v[132:135], v[220:223], v[76:79]
	ds_read_b128 v[250:253], v164 offset:55296
	v_mfma_f32_16x16x32_bf16 v[72:75], v[170:173], v[220:223], v[72:75]
	ds_read_b128 v[150:153], v164 offset:56320
	s_waitcnt lgkmcnt(8)
	v_mfma_f32_16x16x32_bf16 v[116:119], v[174:177], v[192:195], v[116:119]
	s_add_i32 m0, s33, 0x18000
	v_mfma_f32_16x16x32_bf16 v[112:115], v[182:185], v[192:195], v[112:115]
	global_load_lds_dwordx4 v140, s[76:77]
	v_mfma_f32_16x16x32_bf16 v[100:103], v[174:177], v[200:203], v[100:103]
	v_mfma_f32_16x16x32_bf16 v[96:99], v[182:185], v[200:203], v[96:99]
	v_mfma_f32_16x16x32_bf16 v[84:87], v[174:177], v[208:211], v[84:87]
	s_add_i32 m0, s33, 0x1a000
	v_mfma_f32_16x16x32_bf16 v[80:83], v[182:185], v[208:211], v[80:83]
	global_load_lds_dwordx4 v144, s[76:77]
	v_mfma_f32_16x16x32_bf16 v[68:71], v[174:177], v[216:219], v[68:71]
	v_mfma_f32_16x16x32_bf16 v[64:67], v[182:185], v[216:219], v[64:67]
	v_mfma_f32_16x16x32_bf16 v[116:119], v[178:181], v[196:199], v[116:119]
	s_add_u32 s74, s74, 0x80
	s_addc_u32 s75, s75, 0
	v_mfma_f32_16x16x32_bf16 v[112:115], v[188:191], v[196:199], v[112:115]
	s_add_u32 s78, s78, 0x80
	s_addc_u32 s79, s79, 0
	v_mfma_f32_16x16x32_bf16 v[100:103], v[178:181], v[204:207], v[100:103]
	v_mfma_f32_16x16x32_bf16 v[96:99], v[188:191], v[204:207], v[96:99]
	v_mfma_f32_16x16x32_bf16 v[84:87], v[178:181], v[212:215], v[84:87]
	v_mfma_f32_16x16x32_bf16 v[80:83], v[188:191], v[212:215], v[80:83]
	v_mfma_f32_16x16x32_bf16 v[68:71], v[178:181], v[220:223], v[68:71]
	v_mfma_f32_16x16x32_bf16 v[64:67], v[188:191], v[220:223], v[64:67]
	s_waitcnt vmcnt(8) lgkmcnt(0)
	s_barrier
	v_mfma_f32_16x16x32_bf16 v[60:63], v[128:131], v[224:227], v[60:63]
	ds_read_b128 v[192:195], v164 offset:0
	v_mfma_f32_16x16x32_bf16 v[56:59], v[166:169], v[224:227], v[56:59]
	ds_read_b128 v[196:199], v164 offset:1024
	v_mfma_f32_16x16x32_bf16 v[44:47], v[128:131], v[232:235], v[44:47]
	ds_read_b128 v[200:203], v164 offset:2048
	v_mfma_f32_16x16x32_bf16 v[40:43], v[166:169], v[232:235], v[40:43]
	ds_read_b128 v[204:207], v164 offset:3072
	v_mfma_f32_16x16x32_bf16 v[28:31], v[128:131], v[240:243], v[28:31]
	ds_read_b128 v[208:211], v164 offset:4096
	v_mfma_f32_16x16x32_bf16 v[24:27], v[166:169], v[240:243], v[24:27]
	ds_read_b128 v[212:215], v164 offset:5120
	v_mfma_f32_16x16x32_bf16 v[12:15], v[128:131], v[250:253], v[12:15]
	ds_read_b128 v[216:219], v164 offset:6144
	v_mfma_f32_16x16x32_bf16 v[8:11], v[166:169], v[250:253], v[8:11]
	ds_read_b128 v[220:223], v164 offset:7168
	v_mfma_f32_16x16x32_bf16 v[60:63], v[132:135], v[228:231], v[60:63]
	s_add_i32 m0, s33, 0xc000
	v_mfma_f32_16x16x32_bf16 v[56:59], v[170:173], v[228:231], v[56:59]
	global_load_lds_dwordx4 v138, s[74:75]
	v_mfma_f32_16x16x32_bf16 v[44:47], v[132:135], v[236:239], v[44:47]
	v_mfma_f32_16x16x32_bf16 v[40:43], v[170:173], v[236:239], v[40:43]
	v_mfma_f32_16x16x32_bf16 v[28:31], v[132:135], v[244:247], v[28:31]
	s_add_i32 m0, s33, 0xe000
	v_mfma_f32_16x16x32_bf16 v[24:27], v[170:173], v[244:247], v[24:27]
	global_load_lds_dwordx4 v142, s[74:75]
	v_mfma_f32_16x16x32_bf16 v[12:15], v[132:135], v[150:153], v[12:15]
	v_mfma_f32_16x16x32_bf16 v[8:11], v[170:173], v[150:153], v[8:11]
	v_mfma_f32_16x16x32_bf16 v[52:55], v[174:177], v[224:227], v[52:55]
	ds_read_b128 v[128:131], v162 offset:0
	v_mfma_f32_16x16x32_bf16 v[48:51], v[182:185], v[224:227], v[48:51]
	ds_read_b128 v[132:135], v162 offset:1024
	v_mfma_f32_16x16x32_bf16 v[36:39], v[174:177], v[232:235], v[36:39]
	ds_read_b128 v[166:169], v162 offset:2048
	v_mfma_f32_16x16x32_bf16 v[32:35], v[182:185], v[232:235], v[32:35]
	ds_read_b128 v[170:173], v162 offset:3072
	v_mfma_f32_16x16x32_bf16 v[20:23], v[174:177], v[240:243], v[20:23]
	s_add_i32 m0, s33, 0x1c000
	v_mfma_f32_16x16x32_bf16 v[16:19], v[182:185], v[240:243], v[16:19]
	global_load_lds_dwordx4 v140, s[78:79]
	v_mfma_f32_16x16x32_bf16 v[4:7], v[174:177], v[250:253], v[4:7]
	v_mfma_f32_16x16x32_bf16 v[0:3], v[182:185], v[250:253], v[0:3]
	v_mfma_f32_16x16x32_bf16 v[52:55], v[178:181], v[228:231], v[52:55]
	s_add_i32 m0, s33, 0x1e000
	v_mfma_f32_16x16x32_bf16 v[48:51], v[188:191], v[228:231], v[48:51]
	global_load_lds_dwordx4 v144, s[78:79]
	v_mfma_f32_16x16x32_bf16 v[36:39], v[178:181], v[236:239], v[36:39]
	v_mfma_f32_16x16x32_bf16 v[32:35], v[188:191], v[236:239], v[32:35]
	s_add_u32 s72, s72, 0x80
	s_addc_u32 s73, s73, 0
	v_mfma_f32_16x16x32_bf16 v[20:23], v[178:181], v[244:247], v[20:23]
	s_add_u32 s76, s76, 0x80
	s_addc_u32 s77, s77, 0
	v_mfma_f32_16x16x32_bf16 v[16:19], v[188:191], v[244:247], v[16:19]
	v_mfma_f32_16x16x32_bf16 v[4:7], v[178:181], v[150:153], v[4:7]
	v_mfma_f32_16x16x32_bf16 v[0:3], v[188:191], v[150:153], v[0:3]
	s_waitcnt vmcnt(8) lgkmcnt(0)
	s_barrier
	s_mov_b32 s80, 1
	.p2align 6
